# all LRU summary units in the P2 queue (LRU1_N 2048), NA 7
# speedup vs baseline: 1.0011x; 1.0011x over previous
.LBB0_657:
	s_mov_b64 s[14:15], exec
	v_readlane_b32 s16, v254, 17
	v_readlane_b32 s17, v254, 18
	s_and_b64 s[16:17], s[14:15], s[16:17]
	s_mov_b64 exec, s[16:17]
	v_readfirstlane_b32 s18, v252
	s_nop 1
	v_add_u32_e32 v161, s18, v253
	v_mov_b32_e32 v2, s42
	ds_write_b32 v2, v161
	s_or_b64 exec, exec, s[14:15]
	s_waitcnt lgkmcnt(0)
	s_barrier
	ds_read_b32 v2, v169
	s_movk_i32 s14, 0x7ff
	s_waitcnt lgkmcnt(0)
	v_cmp_lt_i32_e64 s[14:15], s14, v2
	v_readfirstlane_b32 s34, v2
	s_and_b64 vcc, exec, s[14:15]
	s_cbranch_vccnz .LBB0_656
	s_mov_b64 s[16:17], exec
	v_readlane_b32 s18, v254, 17
	v_readlane_b32 s19, v254, 18
	s_and_b64 s[18:19], s[16:17], s[18:19]
	s_mov_b64 exec, s[18:19]
	s_cbranch_execz .LBB0_664
	s_mov_b64 s[20:21], exec
	v_mbcnt_lo_u32_b32 v253, s20, 0
	v_mbcnt_hi_u32_b32 v253, s21, v253
	v_cmp_eq_u32_e32 vcc, 0, v253
	s_and_saveexec_b64 s[18:19], vcc
	s_cbranch_execz .LBB0_663
	s_bcnt1_i32_b64 s20, s[20:21]
	v_mov_b32_e32 v252, s20
	global_atomic_add v252, v147, v252, s[76:77] offset:512 sc0

.LBB0_1069:
	v_readlane_b32 s52, v254, 10
	s_cmp_lt_i32 s52, 4
	s_cselect_b64 s[2:3], -1, 0
	s_and_b64 s[20:21], s[2:3], s[0:1]
	v_readlane_b32 s53, v254, 11
	v_readlane_b32 s54, v254, 12
	s_andn2_b64 vcc, exec, s[20:21]
	v_readlane_b32 s55, v254, 13
	s_cbranch_vccnz .LBB0_1396
	s_bitcmp0_b32 s54, 0
	s_cselect_b64 s[0:1], -1, 0
	s_cmpk_gt_i32 s97, -1
	s_cselect_b64 s[2:3], -1, 0
	s_or_b64 s[0:1], s[0:1], s[2:3]
	s_mov_b32 s61, 0
	s_and_b64 vcc, exec, s[0:1]
	s_cbranch_vccnz .LBB0_1147
	s_add_i32 s0, s97, 0x800
	v_and_b32_e32 v146, 48, v1
	v_mov_b32_e32 v147, 0
	s_add_u32 s24, s76, 0x26200000
	v_lshl_add_u64 v[2:3], s[76:77], 0, v[146:147]
	s_mov_b64 s[2:3], 0x500000
	s_addc_u32 s25, s77, 0
	s_movk_i32 s1, 0x200
	v_lshl_add_u64 v[148:149], v[2:3], 0, s[2:3]
	v_lshrrev_b32_e32 v2, 3, v0
	v_lshlrev_b32_e32 v3, 4, v0
	v_cmp_gt_u32_e64 s[8:9], s1, v0
	s_movk_i32 s1, 0x210
	s_add_u32 s37, s76, 0x300000
	v_and_b32_e32 v161, 0x70, v3
	v_mad_u32_u24 v3, v2, s1, 0
	s_addc_u32 s44, s77, 0
	s_ashr_i32 s1, s0, 31
	s_lshl_b64 s[14:15], s[60:61], 12
	s_lshl_b64 s[16:17], s[0:1], 15
	v_add_u32_e32 v162, -3, v2
	v_add_u32_e32 v163, -2, v2
	v_add_u32_e32 v164, -1, v2
	v_cndmask_b32_e64 v165, 0, v2, s[8:9]
	v_lshlrev_b32_e32 v2, 8, v2
	s_add_u32 s1, s16, s14
	v_sub_u32_e32 v2, v3, v2
	s_addc_u32 s15, s17, s15
	v_lshl_add_u32 v167, v161, 1, v2
	v_or_b32_e32 v2, 48, v1
	s_add_u32 s14, s76, s1
	v_add_u32_e32 v6, 0, v146
	v_mul_u32_u24_e32 v7, 0x110, v2
	v_and_b32_e32 v2, 16, v0
	v_lshlrev_b32_e32 v146, 4, v1
	s_addc_u32 s15, s77, s15
	v_and_b32_e32 v4, 15, v0
	v_lshl_add_u32 v166, v161, 2, v3
	v_cmp_eq_u32_e64 s[10:11], 0, v2
	v_lshl_add_u64 v[2:3], s[14:15], 0, v[146:147]
	s_mov_b64 s[14:15], 0x44b00800
	v_lshrrev_b32_e32 v5, 4, v1
	v_lshl_or_b32 v160, s60, 4, v4
	v_lshl_add_u64 v[154:155], v[2:3], 0, s[14:15]
	v_cndmask_b32_e64 v150, 0, 1.0, s[8:9]
	v_mul_u32_u24_e32 v4, 0x110, v4
	v_lshl_add_u32 v8, v160, 2, 0
	v_mul_u32_u24_e32 v5, 0x840, v5
	s_ashr_i32 s97, s96, 31
	s_mov_b32 s38, 0x3e2aaaab
	v_mbcnt_lo_u32_b32 v2, -1, 0
	v_cmp_lt_u32_e64 s[2:3], 23, v0
	v_cmp_lt_u32_e64 s[4:5], 15, v0
	v_cmp_lt_u32_e64 s[6:7], 7, v0
	v_mov_b32_e32 v151, v150
	v_mov_b32_e32 v152, v150
	v_mov_b32_e32 v153, v150
	v_cmp_gt_u32_e64 s[12:13], 16, v1
	s_lshl_b64 s[26:27], s[96:97], 15
	v_readlane_b32 s97, v254, 60
	s_mov_b64 s[28:29], 0x2000
	s_movk_i32 s1, 0x2000
	s_mov_b64 s[30:31], 0x4000
	s_movk_i32 s45, 0x4000
	s_mov_b64 s[34:35], 0x6000
	v_add_u32_e32 v168, v6, v4
	v_add_u32_e32 v169, v6, v7
	s_mov_b32 s46, 0x3f2aaaab
	v_mov_b32_e32 v170, 0x3ecc95a3
	s_mov_b32 s47, 0x3f317218
	s_mov_b32 s48, 0x7f800000
	s_mov_b32 s49, 0x33800000
	s_mov_b32 s50, 0xbe800000
	s_mov_b32 s39, 0x3e124925
	v_mov_b32_e32 v156, 0x3f317218
	v_mov_b32_e32 v171, 0x7f800000
	v_mov_b32_e32 v172, 0x7fc00000
	v_mov_b32_e32 v173, 0xff800000
	v_add_u32_e32 v174, v8, v5
	v_mbcnt_hi_u32_b32 v175, -1, v2
	s_branch .LBB0_1073
